# attention: waves 4-7 defer second sub-tile PV MFMAs across the step barrier (stagger SIMD partners)
# baseline (speedup 1.0000x reference)
.LBB0_115:
	s_lshl_b64 s[4:5], s[42:43], 13
	s_add_u32 s4, s50, s4
	s_addc_u32 s5, s51, s5
	s_lshl_b64 s[8:9], s[42:43], 14
	s_add_u32 s8, s52, s8
	v_lshl_add_u64 v[250:251], s[4:5], 0, v[176:177]
	s_addc_u32 s9, s53, s9
	global_load_dwordx4 v[160:163], v[250:251], off
	v_add_co_u32_e32 v250, vcc, 0x100000, v250
	v_lshl_add_u64 v[252:253], s[8:9], 0, v[176:177]
	s_nop 0
	v_addc_co_u32_e32 v251, vcc, 0, v251, vcc
	global_load_dwordx4 v[168:171], v[250:251], off
	v_add_co_u32_e32 v250, vcc, 0x2000, v252
	global_load_dwordx4 v[164:167], v[252:253], off
	s_nop 0
	v_addc_co_u32_e32 v251, vcc, 0, v253, vcc
	global_load_dwordx4 v[172:175], v[250:251], off

.Lnd_107:
	s_and_b32 s33, s42, 1
	s_mul_i32 s6, s33, 0x9000
	v_add_u32_e32 v199, s6, v187
	v_add_u32_e32 v198, s6, v188
	s_mov_b64 s[54:55], exec
	v_readfirstlane_b32 s4, v186
	s_bitcmp1_b32 s4, 8
	s_cbranch_scc1 .Lab_B
	ds_read_b128 v[202:205], v199
	ds_read_b128 v[206:209], v199 offset:32
	ds_read_b128 v[210:213], v193
	ds_read_b128 v[214:217], v193 offset:32
	ds_read_b128 v[218:221], v199 offset:64
	ds_read_b128 v[222:225], v199 offset:96
	ds_read_b128 v[226:229], v193 offset:64
	ds_read_b128 v[230:233], v193 offset:96
	s_waitcnt lgkmcnt(5)
	v_mfma_f32_32x32x16_bf16 v[144:159], v[202:205], v[210:213], v[0:15]
	s_waitcnt lgkmcnt(4)
	v_mfma_f32_32x32x16_bf16 v[144:159], v[206:209], v[214:217], v[144:159]
	s_waitcnt lgkmcnt(1)
	v_mfma_f32_32x32x16_bf16 v[144:159], v[218:221], v[226:229], v[144:159]
	s_waitcnt lgkmcnt(0)
	v_mfma_f32_32x32x16_bf16 v[144:159], v[222:225], v[230:233], v[144:159]
	s_nop 11
	v_exp_f32_e32 v146, v146
	v_exp_f32_e32 v147, v147
	v_exp_f32_e32 v148, v148
	v_exp_f32_e32 v149, v149
	v_exp_f32_e32 v150, v150
	v_exp_f32_e32 v151, v151
	v_exp_f32_e32 v152, v152
	v_exp_f32_e32 v153, v153
	v_exp_f32_e32 v144, v144
	v_exp_f32_e32 v154, v154
	v_exp_f32_e32 v145, v145
	v_exp_f32_e32 v155, v155
	v_add_f32_e32 v201, 0, v144
	v_exp_f32_e32 v156, v156
	v_add_f32_e32 v201, v145, v201
	v_add_f32_e32 v201, v146, v201
	v_add_f32_e32 v201, v147, v201
	v_exp_f32_e32 v157, v157
	v_add_f32_e32 v201, v148, v201
	v_add_f32_e32 v201, v149, v201
	v_add_f32_e32 v201, v150, v201
	v_exp_f32_e32 v158, v158
	v_add_f32_e32 v201, v151, v201
	v_add_f32_e32 v201, v152, v201
	v_add_f32_e32 v201, v153, v201
	v_exp_f32_e32 v159, v159
	v_add_f32_e32 v201, v154, v201
	v_add_f32_e32 v201, v155, v201
	v_add_f32_e32 v201, v156, v201
	v_add_f32_e32 v201, v157, v201
	v_add_f32_e32 v201, v158, v201
	v_cvt_pk_bf16_f32 v202, v144, v145
	v_add_f32_e32 v144, v159, v201
	v_add_f32_e32 v196, v196, v144
	v_cvt_pk_bf16_f32 v203, v146, v147
	v_cvt_pk_bf16_f32 v204, v148, v149
	v_cvt_pk_bf16_f32 v205, v150, v151
	v_cvt_pk_bf16_f32 v206, v152, v153
	v_cvt_pk_bf16_f32 v207, v154, v155
	v_cvt_pk_bf16_f32 v208, v156, v157
	v_cvt_pk_bf16_f32 v209, v158, v159
	ds_read_b128 v[210:213], v199 offset:9216
	ds_read_b128 v[214:217], v199 offset:9248
	ds_read_b128 v[218:221], v193 offset:36864
	ds_read_b128 v[222:225], v193 offset:36896
	ds_read_b128 v[226:229], v199 offset:9280
	ds_read_b128 v[230:233], v199 offset:9312
	ds_read_b128 v[234:237], v193 offset:36928
	ds_read_b128 v[238:241], v193 offset:36960
	s_waitcnt lgkmcnt(5)
	v_mfma_f32_32x32x16_bf16 v[144:159], v[210:213], v[218:221], v[0:15]
	s_waitcnt lgkmcnt(4)
	v_mfma_f32_32x32x16_bf16 v[144:159], v[214:217], v[222:225], v[144:159]
	ds_read_b128 v[210:213], v198
	ds_read_b128 v[214:217], v198 offset:32
	ds_read_b128 v[218:221], v198 offset:4608
	ds_read_b128 v[222:225], v198 offset:4640
	s_waitcnt lgkmcnt(5)
	v_mfma_f32_32x32x16_bf16 v[144:159], v[226:229], v[234:237], v[144:159]
	s_waitcnt lgkmcnt(4)
	v_mfma_f32_32x32x16_bf16 v[144:159], v[230:233], v[238:241], v[144:159]
	s_nop 11
	v_exp_f32_e32 v144, v144
	v_exp_f32_e32 v145, v145
	v_exp_f32_e32 v146, v146
	v_exp_f32_e32 v147, v147
	v_exp_f32_e32 v148, v148
	v_exp_f32_e32 v149, v149
	v_add_f32_e32 v201, 0, v144
	v_exp_f32_e32 v150, v150
	v_add_f32_e32 v201, v145, v201
	v_exp_f32_e32 v151, v151
	v_add_f32_e32 v201, v146, v201
	v_exp_f32_e32 v152, v152
	v_add_f32_e32 v201, v147, v201
	v_exp_f32_e32 v153, v153
	v_add_f32_e32 v201, v148, v201
	v_exp_f32_e32 v154, v154
	v_add_f32_e32 v201, v149, v201
	v_exp_f32_e32 v155, v155
	v_add_f32_e32 v201, v150, v201
	v_exp_f32_e32 v156, v156
	v_add_f32_e32 v201, v151, v201
	v_exp_f32_e32 v157, v157
	v_add_f32_e32 v201, v152, v201
	v_exp_f32_e32 v158, v158
	v_add_f32_e32 v201, v153, v201
	v_exp_f32_e32 v159, v159
	v_add_f32_e32 v201, v154, v201
	v_add_f32_e32 v201, v155, v201
	v_add_f32_e32 v201, v156, v201
	v_add_f32_e32 v201, v157, v201
	v_add_f32_e32 v201, v158, v201
	v_cvt_pk_bf16_f32 v144, v144, v145
	v_cvt_pk_bf16_f32 v145, v146, v147
	v_cvt_pk_bf16_f32 v146, v148, v149
	v_cvt_pk_bf16_f32 v147, v150, v151
	v_cvt_pk_bf16_f32 v148, v152, v153
	v_cvt_pk_bf16_f32 v149, v154, v155
	v_cvt_pk_bf16_f32 v150, v156, v157
	v_cvt_pk_bf16_f32 v151, v158, v159
	v_add_f32_e32 v201, v159, v201
	ds_read_b128 v[152:155], v198 offset:9216
	ds_read_b128 v[156:159], v198 offset:9248
	ds_read_b128 v[226:229], v198 offset:13824
	ds_read_b128 v[230:233], v198 offset:13856
	s_waitcnt lgkmcnt(7)
	v_mfma_f32_32x32x16_bf16 v[112:127], v[210:213], v[202:205], v[112:127]
	v_mfma_f32_32x32x16_bf16 v[128:143], v[210:213], v[144:147], v[128:143]
	s_waitcnt lgkmcnt(5)
	v_mfma_f32_32x32x16_bf16 v[80:95], v[218:221], v[202:205], v[80:95]
	v_mfma_f32_32x32x16_bf16 v[96:111], v[218:221], v[144:147], v[96:111]
	v_mfma_f32_32x32x16_bf16 v[112:127], v[214:217], v[206:209], v[112:127]
	v_mfma_f32_32x32x16_bf16 v[128:143], v[214:217], v[148:151], v[128:143]
	s_waitcnt lgkmcnt(4)
	v_mfma_f32_32x32x16_bf16 v[80:95], v[222:225], v[206:209], v[80:95]
	v_mfma_f32_32x32x16_bf16 v[96:111], v[222:225], v[148:151], v[96:111]
	s_waitcnt lgkmcnt(3)
	v_mfma_f32_32x32x16_bf16 v[48:63], v[152:155], v[202:205], v[48:63]
	v_add_f32_e32 v197, v197, v201
	v_mfma_f32_32x32x16_bf16 v[64:79], v[152:155], v[144:147], v[64:79]
	s_waitcnt lgkmcnt(1)
	v_mfma_f32_32x32x16_bf16 v[16:31], v[226:229], v[202:205], v[16:31]
	v_mfma_f32_32x32x16_bf16 v[32:47], v[226:229], v[144:147], v[32:47]
	v_mfma_f32_32x32x16_bf16 v[48:63], v[156:159], v[206:209], v[48:63]
	v_mfma_f32_32x32x16_bf16 v[64:79], v[156:159], v[148:151], v[64:79]
	s_waitcnt lgkmcnt(0)
	v_mfma_f32_32x32x16_bf16 v[16:31], v[230:233], v[206:209], v[16:31]
	v_mfma_f32_32x32x16_bf16 v[32:47], v[230:233], v[148:151], v[32:47]
	ds_read_b128 v[202:205], v199 offset:4608
	ds_read_b128 v[206:209], v199 offset:4640
	ds_read_b128 v[210:213], v193
	ds_read_b128 v[214:217], v193 offset:32
	ds_read_b128 v[218:221], v199 offset:4672
	ds_read_b128 v[222:225], v199 offset:4704
	ds_read_b128 v[226:229], v193 offset:64
	ds_read_b128 v[230:233], v193 offset:96
	s_waitcnt lgkmcnt(5)
	v_mfma_f32_32x32x16_bf16 v[144:159], v[202:205], v[210:213], v[0:15]
	s_waitcnt lgkmcnt(4)
	v_mfma_f32_32x32x16_bf16 v[144:159], v[206:209], v[214:217], v[144:159]
	s_waitcnt lgkmcnt(1)
	v_mfma_f32_32x32x16_bf16 v[144:159], v[218:221], v[226:229], v[144:159]
	s_waitcnt lgkmcnt(0)
	v_mfma_f32_32x32x16_bf16 v[144:159], v[222:225], v[230:233], v[144:159]
	s_nop 11
	v_exp_f32_e32 v146, v146
	v_exp_f32_e32 v147, v147
	v_exp_f32_e32 v148, v148
	v_exp_f32_e32 v149, v149
	v_exp_f32_e32 v150, v150
	v_exp_f32_e32 v151, v151
	v_exp_f32_e32 v152, v152
	v_exp_f32_e32 v153, v153
	v_exp_f32_e32 v144, v144
	v_exp_f32_e32 v145, v145
	v_exp_f32_e32 v154, v154
	v_exp_f32_e32 v155, v155
	v_add_f32_e32 v201, 0, v144
	v_add_f32_e32 v201, v145, v201
	v_add_f32_e32 v201, v146, v201
	v_exp_f32_e32 v156, v156
	v_add_f32_e32 v201, v147, v201
	v_add_f32_e32 v201, v148, v201
	v_add_f32_e32 v201, v149, v201
	v_exp_f32_e32 v157, v157
	v_add_f32_e32 v201, v150, v201
	v_add_f32_e32 v201, v151, v201
	v_add_f32_e32 v201, v152, v201
	v_exp_f32_e32 v158, v158
	v_add_f32_e32 v201, v153, v201
	v_exp_f32_e32 v159, v159
	v_add_f32_e32 v201, v154, v201
	v_add_f32_e32 v201, v155, v201
	v_add_f32_e32 v201, v156, v201
	v_add_f32_e32 v201, v157, v201
	v_add_f32_e32 v208, v158, v201
	v_cvt_pk_bf16_f32 v200, v144, v145
	v_add_f32_e32 v144, v159, v208
	v_add_f32_e32 v196, v196, v144
	v_cvt_pk_bf16_f32 v201, v146, v147
	v_cvt_pk_bf16_f32 v202, v148, v149
	v_cvt_pk_bf16_f32 v203, v150, v151
	v_cvt_pk_bf16_f32 v204, v152, v153
	v_cvt_pk_bf16_f32 v205, v154, v155
	v_cvt_pk_bf16_f32 v206, v156, v157
	v_cvt_pk_bf16_f32 v207, v158, v159
	ds_read_b128 v[208:211], v199 offset:13824
	ds_read_b128 v[212:215], v199 offset:13856
	ds_read_b128 v[216:219], v193 offset:36864
	ds_read_b128 v[220:223], v193 offset:36896
	ds_read_b128 v[224:227], v199 offset:13888
	ds_read_b128 v[228:231], v199 offset:13920
	ds_read_b128 v[232:235], v193 offset:36928
	ds_read_b128 v[236:239], v193 offset:36960
	s_waitcnt lgkmcnt(5)
	v_mfma_f32_32x32x16_bf16 v[144:159], v[208:211], v[216:219], v[0:15]
	s_waitcnt lgkmcnt(4)
	v_mfma_f32_32x32x16_bf16 v[144:159], v[212:215], v[220:223], v[144:159]
	ds_read_b128 v[208:211], v198 offset:64
	ds_read_b128 v[212:215], v198 offset:96
	ds_read_b128 v[216:219], v198 offset:4672
	ds_read_b128 v[220:223], v198 offset:4704
	s_waitcnt lgkmcnt(5)
	v_mfma_f32_32x32x16_bf16 v[144:159], v[224:227], v[232:235], v[144:159]
	s_waitcnt lgkmcnt(4)
	v_mfma_f32_32x32x16_bf16 v[144:159], v[228:231], v[236:239], v[144:159]
	s_nop 11
	v_exp_f32_e32 v144, v144
	v_exp_f32_e32 v145, v145
	v_exp_f32_e32 v146, v146
	v_exp_f32_e32 v147, v147
	v_exp_f32_e32 v148, v148
	v_exp_f32_e32 v149, v149
	v_add_f32_e32 v199, 0, v144
	v_exp_f32_e32 v150, v150
	v_add_f32_e32 v199, v145, v199
	v_exp_f32_e32 v151, v151
	v_add_f32_e32 v199, v146, v199
	v_exp_f32_e32 v152, v152
	v_add_f32_e32 v199, v147, v199
	v_exp_f32_e32 v153, v153
	v_add_f32_e32 v199, v148, v199
	v_exp_f32_e32 v154, v154
	v_add_f32_e32 v199, v149, v199
	v_exp_f32_e32 v155, v155
	v_add_f32_e32 v199, v150, v199
	v_exp_f32_e32 v156, v156
	v_add_f32_e32 v199, v151, v199
	v_exp_f32_e32 v157, v157
	v_add_f32_e32 v199, v152, v199
	v_exp_f32_e32 v158, v158
	v_add_f32_e32 v199, v153, v199
	v_exp_f32_e32 v159, v159
	v_add_f32_e32 v199, v154, v199
	v_add_f32_e32 v199, v155, v199
	v_add_f32_e32 v199, v156, v199
	v_add_f32_e32 v199, v157, v199
	v_add_f32_e32 v199, v158, v199
	v_cvt_pk_bf16_f32 v144, v144, v145
	v_cvt_pk_bf16_f32 v145, v146, v147
	v_cvt_pk_bf16_f32 v146, v148, v149
	v_cvt_pk_bf16_f32 v147, v150, v151
	v_cvt_pk_bf16_f32 v148, v152, v153
	v_cvt_pk_bf16_f32 v149, v154, v155
	v_cvt_pk_bf16_f32 v150, v156, v157
	v_cvt_pk_bf16_f32 v151, v158, v159
	v_add_f32_e32 v199, v159, v199
	ds_read_b128 v[152:155], v198 offset:9280
	ds_read_b128 v[156:159], v198 offset:9312
	ds_read_b128 v[224:227], v198 offset:13888
	ds_read_b128 v[228:231], v198 offset:13920
	v_add_f32_e32 v197, v197, v199
	s_waitcnt lgkmcnt(7)
	v_mfma_f32_32x32x16_bf16 v[112:127], v[208:211], v[200:203], v[112:127]
	v_mfma_f32_32x32x16_bf16 v[128:143], v[208:211], v[144:147], v[128:143]
	s_waitcnt lgkmcnt(5)
	v_mfma_f32_32x32x16_bf16 v[80:95], v[216:219], v[200:203], v[80:95]
	v_mfma_f32_32x32x16_bf16 v[96:111], v[216:219], v[144:147], v[96:111]
	v_mfma_f32_32x32x16_bf16 v[112:127], v[212:215], v[204:207], v[112:127]
	v_mfma_f32_32x32x16_bf16 v[128:143], v[212:215], v[148:151], v[128:143]
	s_waitcnt lgkmcnt(4)
	v_mfma_f32_32x32x16_bf16 v[80:95], v[220:223], v[204:207], v[80:95]
	v_mfma_f32_32x32x16_bf16 v[96:111], v[220:223], v[148:151], v[96:111]
	s_waitcnt lgkmcnt(3)
	v_mfma_f32_32x32x16_bf16 v[48:63], v[152:155], v[200:203], v[48:63]
	v_mfma_f32_32x32x16_bf16 v[64:79], v[152:155], v[144:147], v[64:79]
	s_waitcnt lgkmcnt(1)
	v_mfma_f32_32x32x16_bf16 v[16:31], v[224:227], v[200:203], v[16:31]
	v_mfma_f32_32x32x16_bf16 v[32:47], v[224:227], v[144:147], v[32:47]
	v_mfma_f32_32x32x16_bf16 v[48:63], v[156:159], v[204:207], v[48:63]
	v_mfma_f32_32x32x16_bf16 v[64:79], v[156:159], v[148:151], v[64:79]
	s_waitcnt lgkmcnt(0)
	v_mfma_f32_32x32x16_bf16 v[16:31], v[228:231], v[204:207], v[16:31]
	v_mfma_f32_32x32x16_bf16 v[32:47], v[228:231], v[148:151], v[32:47]
	s_branch .LBB0_111
.Lab_B:
	s_cmp_eq_u32 s42, 0
	s_cbranch_scc1 .Lab_B0
	s_waitcnt lgkmcnt(7)
	v_mfma_f32_32x32x16_bf16 v[112:127], v[208:211], v[200:203], v[112:127]
	v_mfma_f32_32x32x16_bf16 v[128:143], v[208:211], v[144:147], v[128:143]
	s_waitcnt lgkmcnt(5)
	v_mfma_f32_32x32x16_bf16 v[80:95], v[216:219], v[200:203], v[80:95]
	v_mfma_f32_32x32x16_bf16 v[96:111], v[216:219], v[144:147], v[96:111]
	v_mfma_f32_32x32x16_bf16 v[112:127], v[212:215], v[204:207], v[112:127]
	v_mfma_f32_32x32x16_bf16 v[128:143], v[212:215], v[148:151], v[128:143]
	s_waitcnt lgkmcnt(4)
	v_mfma_f32_32x32x16_bf16 v[80:95], v[220:223], v[204:207], v[80:95]
	v_mfma_f32_32x32x16_bf16 v[96:111], v[220:223], v[148:151], v[96:111]
	s_waitcnt lgkmcnt(3)
	v_mfma_f32_32x32x16_bf16 v[48:63], v[152:155], v[200:203], v[48:63]
	v_mfma_f32_32x32x16_bf16 v[64:79], v[152:155], v[144:147], v[64:79]
	s_waitcnt lgkmcnt(1)
	v_mfma_f32_32x32x16_bf16 v[16:31], v[224:227], v[200:203], v[16:31]
	v_mfma_f32_32x32x16_bf16 v[32:47], v[224:227], v[144:147], v[32:47]
	v_mfma_f32_32x32x16_bf16 v[48:63], v[156:159], v[204:207], v[48:63]
	v_mfma_f32_32x32x16_bf16 v[64:79], v[156:159], v[148:151], v[64:79]
	s_waitcnt lgkmcnt(0)
	v_mfma_f32_32x32x16_bf16 v[16:31], v[228:231], v[204:207], v[16:31]
	v_mfma_f32_32x32x16_bf16 v[32:47], v[228:231], v[148:151], v[32:47]
.Lab_B0:
	ds_read_b128 v[202:205], v199
	ds_read_b128 v[206:209], v199 offset:32
	ds_read_b128 v[210:213], v193
	ds_read_b128 v[214:217], v193 offset:32
	ds_read_b128 v[218:221], v199 offset:64
	ds_read_b128 v[222:225], v199 offset:96
	ds_read_b128 v[226:229], v193 offset:64
	ds_read_b128 v[230:233], v193 offset:96
	s_waitcnt lgkmcnt(5)
	v_mfma_f32_32x32x16_bf16 v[144:159], v[202:205], v[210:213], v[0:15]
	s_waitcnt lgkmcnt(4)
	v_mfma_f32_32x32x16_bf16 v[144:159], v[206:209], v[214:217], v[144:159]
	s_waitcnt lgkmcnt(1)
	v_mfma_f32_32x32x16_bf16 v[144:159], v[218:221], v[226:229], v[144:159]
	s_waitcnt lgkmcnt(0)
	v_mfma_f32_32x32x16_bf16 v[144:159], v[222:225], v[230:233], v[144:159]
	s_nop 11
	v_exp_f32_e32 v146, v146
	v_exp_f32_e32 v147, v147
	v_exp_f32_e32 v148, v148
	v_exp_f32_e32 v149, v149
	v_exp_f32_e32 v150, v150
	v_exp_f32_e32 v151, v151
	v_exp_f32_e32 v152, v152
	v_exp_f32_e32 v153, v153
	v_exp_f32_e32 v144, v144
	v_exp_f32_e32 v154, v154
	v_exp_f32_e32 v145, v145
	v_exp_f32_e32 v155, v155
	v_add_f32_e32 v201, 0, v144
	v_exp_f32_e32 v156, v156
	v_add_f32_e32 v201, v145, v201
	v_add_f32_e32 v201, v146, v201
	v_add_f32_e32 v201, v147, v201
	v_exp_f32_e32 v157, v157
	v_add_f32_e32 v201, v148, v201
	v_add_f32_e32 v201, v149, v201
	v_add_f32_e32 v201, v150, v201
	v_exp_f32_e32 v158, v158
	v_add_f32_e32 v201, v151, v201
	v_add_f32_e32 v201, v152, v201
	v_add_f32_e32 v201, v153, v201
	v_exp_f32_e32 v159, v159
	v_add_f32_e32 v201, v154, v201
	v_add_f32_e32 v201, v155, v201
	v_add_f32_e32 v201, v156, v201
	v_add_f32_e32 v201, v157, v201
	v_add_f32_e32 v201, v158, v201
	v_cvt_pk_bf16_f32 v202, v144, v145
	v_add_f32_e32 v144, v159, v201
	v_add_f32_e32 v196, v196, v144
	v_cvt_pk_bf16_f32 v203, v146, v147
	v_cvt_pk_bf16_f32 v204, v148, v149
	v_cvt_pk_bf16_f32 v205, v150, v151
	v_cvt_pk_bf16_f32 v206, v152, v153
	v_cvt_pk_bf16_f32 v207, v154, v155
	v_cvt_pk_bf16_f32 v208, v156, v157
	v_cvt_pk_bf16_f32 v209, v158, v159
	ds_read_b128 v[210:213], v199 offset:9216
	ds_read_b128 v[214:217], v199 offset:9248
	ds_read_b128 v[218:221], v193 offset:36864
	ds_read_b128 v[222:225], v193 offset:36896
	ds_read_b128 v[226:229], v199 offset:9280
	ds_read_b128 v[230:233], v199 offset:9312
	ds_read_b128 v[234:237], v193 offset:36928
	ds_read_b128 v[238:241], v193 offset:36960
	s_waitcnt lgkmcnt(5)
	v_mfma_f32_32x32x16_bf16 v[144:159], v[210:213], v[218:221], v[0:15]
	s_waitcnt lgkmcnt(4)
	v_mfma_f32_32x32x16_bf16 v[144:159], v[214:217], v[222:225], v[144:159]
	ds_read_b128 v[210:213], v198
	ds_read_b128 v[214:217], v198 offset:32
	ds_read_b128 v[218:221], v198 offset:4608
	ds_read_b128 v[222:225], v198 offset:4640
	s_waitcnt lgkmcnt(5)
	v_mfma_f32_32x32x16_bf16 v[144:159], v[226:229], v[234:237], v[144:159]
	s_waitcnt lgkmcnt(4)
	v_mfma_f32_32x32x16_bf16 v[144:159], v[230:233], v[238:241], v[144:159]
	s_nop 11
	v_exp_f32_e32 v144, v144
	v_exp_f32_e32 v145, v145
	v_exp_f32_e32 v146, v146
	v_exp_f32_e32 v147, v147
	v_exp_f32_e32 v148, v148
	v_exp_f32_e32 v149, v149
	v_add_f32_e32 v201, 0, v144
	v_exp_f32_e32 v150, v150
	v_add_f32_e32 v201, v145, v201
	v_exp_f32_e32 v151, v151
	v_add_f32_e32 v201, v146, v201
	v_exp_f32_e32 v152, v152
	v_add_f32_e32 v201, v147, v201
	v_exp_f32_e32 v153, v153
	v_add_f32_e32 v201, v148, v201
	v_exp_f32_e32 v154, v154
	v_add_f32_e32 v201, v149, v201
	v_exp_f32_e32 v155, v155
	v_add_f32_e32 v201, v150, v201
	v_exp_f32_e32 v156, v156
	v_add_f32_e32 v201, v151, v201
	v_exp_f32_e32 v157, v157
	v_add_f32_e32 v201, v152, v201
	v_exp_f32_e32 v158, v158
	v_add_f32_e32 v201, v153, v201
	v_exp_f32_e32 v159, v159
	v_add_f32_e32 v201, v154, v201
	v_add_f32_e32 v201, v155, v201
	v_add_f32_e32 v201, v156, v201
	v_add_f32_e32 v201, v157, v201
	v_add_f32_e32 v201, v158, v201
	v_cvt_pk_bf16_f32 v144, v144, v145
	v_cvt_pk_bf16_f32 v145, v146, v147
	v_cvt_pk_bf16_f32 v146, v148, v149
	v_cvt_pk_bf16_f32 v147, v150, v151
	v_cvt_pk_bf16_f32 v148, v152, v153
	v_cvt_pk_bf16_f32 v149, v154, v155
	v_cvt_pk_bf16_f32 v150, v156, v157
	v_cvt_pk_bf16_f32 v151, v158, v159
	v_add_f32_e32 v201, v159, v201
	ds_read_b128 v[152:155], v198 offset:9216
	ds_read_b128 v[156:159], v198 offset:9248
	ds_read_b128 v[226:229], v198 offset:13824
	ds_read_b128 v[230:233], v198 offset:13856
	s_waitcnt lgkmcnt(7)
	v_mfma_f32_32x32x16_bf16 v[112:127], v[210:213], v[202:205], v[112:127]
	v_mfma_f32_32x32x16_bf16 v[128:143], v[210:213], v[144:147], v[128:143]
	s_waitcnt lgkmcnt(5)
	v_mfma_f32_32x32x16_bf16 v[80:95], v[218:221], v[202:205], v[80:95]
	v_mfma_f32_32x32x16_bf16 v[96:111], v[218:221], v[144:147], v[96:111]
	v_mfma_f32_32x32x16_bf16 v[112:127], v[214:217], v[206:209], v[112:127]
	v_mfma_f32_32x32x16_bf16 v[128:143], v[214:217], v[148:151], v[128:143]
	s_waitcnt lgkmcnt(4)
	v_mfma_f32_32x32x16_bf16 v[80:95], v[222:225], v[206:209], v[80:95]
	v_mfma_f32_32x32x16_bf16 v[96:111], v[222:225], v[148:151], v[96:111]
	s_waitcnt lgkmcnt(3)
	v_mfma_f32_32x32x16_bf16 v[48:63], v[152:155], v[202:205], v[48:63]
	v_add_f32_e32 v197, v197, v201
	v_mfma_f32_32x32x16_bf16 v[64:79], v[152:155], v[144:147], v[64:79]
	s_waitcnt lgkmcnt(1)
	v_mfma_f32_32x32x16_bf16 v[16:31], v[226:229], v[202:205], v[16:31]
	v_mfma_f32_32x32x16_bf16 v[32:47], v[226:229], v[144:147], v[32:47]
	v_mfma_f32_32x32x16_bf16 v[48:63], v[156:159], v[206:209], v[48:63]
	v_mfma_f32_32x32x16_bf16 v[64:79], v[156:159], v[148:151], v[64:79]
	s_waitcnt lgkmcnt(0)
	v_mfma_f32_32x32x16_bf16 v[16:31], v[230:233], v[206:209], v[16:31]
	v_mfma_f32_32x32x16_bf16 v[32:47], v[230:233], v[148:151], v[32:47]
	ds_read_b128 v[202:205], v199 offset:4608
	ds_read_b128 v[206:209], v199 offset:4640
	ds_read_b128 v[210:213], v193
	ds_read_b128 v[214:217], v193 offset:32
	ds_read_b128 v[218:221], v199 offset:4672
	ds_read_b128 v[222:225], v199 offset:4704
	ds_read_b128 v[226:229], v193 offset:64
	ds_read_b128 v[230:233], v193 offset:96
	s_waitcnt lgkmcnt(5)
	v_mfma_f32_32x32x16_bf16 v[144:159], v[202:205], v[210:213], v[0:15]
	s_waitcnt lgkmcnt(4)
	v_mfma_f32_32x32x16_bf16 v[144:159], v[206:209], v[214:217], v[144:159]
	s_waitcnt lgkmcnt(1)
	v_mfma_f32_32x32x16_bf16 v[144:159], v[218:221], v[226:229], v[144:159]
	s_waitcnt lgkmcnt(0)
	v_mfma_f32_32x32x16_bf16 v[144:159], v[222:225], v[230:233], v[144:159]
	s_nop 11
	v_exp_f32_e32 v146, v146
	v_exp_f32_e32 v147, v147
	v_exp_f32_e32 v148, v148
	v_exp_f32_e32 v149, v149
	v_exp_f32_e32 v150, v150
	v_exp_f32_e32 v151, v151
	v_exp_f32_e32 v152, v152
	v_exp_f32_e32 v153, v153
	v_exp_f32_e32 v144, v144
	v_exp_f32_e32 v145, v145
	v_exp_f32_e32 v154, v154
	v_exp_f32_e32 v155, v155
	v_add_f32_e32 v201, 0, v144
	v_add_f32_e32 v201, v145, v201
	v_add_f32_e32 v201, v146, v201
	v_exp_f32_e32 v156, v156
	v_add_f32_e32 v201, v147, v201
	v_add_f32_e32 v201, v148, v201
	v_add_f32_e32 v201, v149, v201
	v_exp_f32_e32 v157, v157
	v_add_f32_e32 v201, v150, v201
	v_add_f32_e32 v201, v151, v201
	v_add_f32_e32 v201, v152, v201
	v_exp_f32_e32 v158, v158
	v_add_f32_e32 v201, v153, v201
	v_exp_f32_e32 v159, v159
	v_add_f32_e32 v201, v154, v201
	v_add_f32_e32 v201, v155, v201
	v_add_f32_e32 v201, v156, v201
	v_add_f32_e32 v201, v157, v201
	v_add_f32_e32 v208, v158, v201
	v_cvt_pk_bf16_f32 v200, v144, v145
	v_add_f32_e32 v144, v159, v208
	v_add_f32_e32 v196, v196, v144
	v_cvt_pk_bf16_f32 v201, v146, v147
	v_cvt_pk_bf16_f32 v202, v148, v149
	v_cvt_pk_bf16_f32 v203, v150, v151
	v_cvt_pk_bf16_f32 v204, v152, v153
	v_cvt_pk_bf16_f32 v205, v154, v155
	v_cvt_pk_bf16_f32 v206, v156, v157
	v_cvt_pk_bf16_f32 v207, v158, v159
	ds_read_b128 v[208:211], v199 offset:13824
	ds_read_b128 v[212:215], v199 offset:13856
	ds_read_b128 v[216:219], v193 offset:36864
	ds_read_b128 v[220:223], v193 offset:36896
	ds_read_b128 v[224:227], v199 offset:13888
	ds_read_b128 v[228:231], v199 offset:13920
	ds_read_b128 v[232:235], v193 offset:36928
	ds_read_b128 v[236:239], v193 offset:36960
	s_waitcnt lgkmcnt(5)
	v_mfma_f32_32x32x16_bf16 v[144:159], v[208:211], v[216:219], v[0:15]
	s_waitcnt lgkmcnt(4)
	v_mfma_f32_32x32x16_bf16 v[144:159], v[212:215], v[220:223], v[144:159]
	ds_read_b128 v[208:211], v198 offset:64
	ds_read_b128 v[212:215], v198 offset:96
	ds_read_b128 v[216:219], v198 offset:4672
	ds_read_b128 v[220:223], v198 offset:4704
	s_waitcnt lgkmcnt(5)
	v_mfma_f32_32x32x16_bf16 v[144:159], v[224:227], v[232:235], v[144:159]
	s_waitcnt lgkmcnt(4)
	v_mfma_f32_32x32x16_bf16 v[144:159], v[228:231], v[236:239], v[144:159]
	s_nop 11
	v_exp_f32_e32 v144, v144
	v_exp_f32_e32 v145, v145
	v_exp_f32_e32 v146, v146
	v_exp_f32_e32 v147, v147
	v_exp_f32_e32 v148, v148
	v_exp_f32_e32 v149, v149
	v_add_f32_e32 v199, 0, v144
	v_exp_f32_e32 v150, v150
	v_add_f32_e32 v199, v145, v199
	v_exp_f32_e32 v151, v151
	v_add_f32_e32 v199, v146, v199
	v_exp_f32_e32 v152, v152
	v_add_f32_e32 v199, v147, v199
	v_exp_f32_e32 v153, v153
	v_add_f32_e32 v199, v148, v199
	v_exp_f32_e32 v154, v154
	v_add_f32_e32 v199, v149, v199
	v_exp_f32_e32 v155, v155
	v_add_f32_e32 v199, v150, v199
	v_exp_f32_e32 v156, v156
	v_add_f32_e32 v199, v151, v199
	v_exp_f32_e32 v157, v157
	v_add_f32_e32 v199, v152, v199
	v_exp_f32_e32 v158, v158
	v_add_f32_e32 v199, v153, v199
	v_exp_f32_e32 v159, v159
	v_add_f32_e32 v199, v154, v199
	v_add_f32_e32 v199, v155, v199
	v_add_f32_e32 v199, v156, v199
	v_add_f32_e32 v199, v157, v199
	v_add_f32_e32 v199, v158, v199
	v_cvt_pk_bf16_f32 v144, v144, v145
	v_cvt_pk_bf16_f32 v145, v146, v147
	v_cvt_pk_bf16_f32 v146, v148, v149
	v_cvt_pk_bf16_f32 v147, v150, v151
	v_cvt_pk_bf16_f32 v148, v152, v153
	v_cvt_pk_bf16_f32 v149, v154, v155
	v_cvt_pk_bf16_f32 v150, v156, v157
	v_cvt_pk_bf16_f32 v151, v158, v159
	v_add_f32_e32 v199, v159, v199
	ds_read_b128 v[152:155], v198 offset:9280
	ds_read_b128 v[156:159], v198 offset:9312
	ds_read_b128 v[224:227], v198 offset:13888
	ds_read_b128 v[228:231], v198 offset:13920
	v_add_f32_e32 v197, v197, v199
	s_add_i32 s4, s42, 1
	s_cmp_lt_u32 s4, s98
	s_cbranch_scc1 .LBB0_111
	s_waitcnt lgkmcnt(7)
	v_mfma_f32_32x32x16_bf16 v[112:127], v[208:211], v[200:203], v[112:127]
	v_mfma_f32_32x32x16_bf16 v[128:143], v[208:211], v[144:147], v[128:143]
	s_waitcnt lgkmcnt(5)
	v_mfma_f32_32x32x16_bf16 v[80:95], v[216:219], v[200:203], v[80:95]
	v_mfma_f32_32x32x16_bf16 v[96:111], v[216:219], v[144:147], v[96:111]
	v_mfma_f32_32x32x16_bf16 v[112:127], v[212:215], v[204:207], v[112:127]
	v_mfma_f32_32x32x16_bf16 v[128:143], v[212:215], v[148:151], v[128:143]
	s_waitcnt lgkmcnt(4)
	v_mfma_f32_32x32x16_bf16 v[80:95], v[220:223], v[204:207], v[80:95]
	v_mfma_f32_32x32x16_bf16 v[96:111], v[220:223], v[148:151], v[96:111]
	s_waitcnt lgkmcnt(3)
	v_mfma_f32_32x32x16_bf16 v[48:63], v[152:155], v[200:203], v[48:63]
	v_mfma_f32_32x32x16_bf16 v[64:79], v[152:155], v[144:147], v[64:79]
	s_waitcnt lgkmcnt(1)
	v_mfma_f32_32x32x16_bf16 v[16:31], v[224:227], v[200:203], v[16:31]
	v_mfma_f32_32x32x16_bf16 v[32:47], v[224:227], v[144:147], v[32:47]
	v_mfma_f32_32x32x16_bf16 v[48:63], v[156:159], v[204:207], v[48:63]
	v_mfma_f32_32x32x16_bf16 v[64:79], v[156:159], v[148:151], v[64:79]
	s_waitcnt lgkmcnt(0)
	v_mfma_f32_32x32x16_bf16 v[16:31], v[228:231], v[204:207], v[16:31]
	v_mfma_f32_32x32x16_bf16 v[32:47], v[228:231], v[148:151], v[32:47]
	s_branch .LBB0_111

.LBB0_119:
	v_add_u32_e32 v250, 0x9000, v190
	s_waitcnt vmcnt(3)
	ds_write_b128 v189, v[160:163] offset:36864
	s_waitcnt vmcnt(1)
	ds_write2_b64 v250, v[164:165], v[166:167] offset1:2
	ds_write_b128 v189, v[168:171] offset:46080
	v_add_u32_e32 v250, 0xb000, v190
	s_waitcnt vmcnt(0)
	ds_write2_b64 v250, v[172:173], v[174:175] offset0:128 offset1:130
	s_add_i32 s42, s42, 2
	s_cmp_ge_u32 s42, s99
	s_cbranch_scc0 .LBB0_115
	s_branch .LBB0_116
